# phase B: odd one-conv prompt blocks run their strips/attention item before the conv item (conv bursts of the two halves no longer coincide)
# speedup vs baseline: 1.0598x; 1.0018x over previous
.LBB0_319:
	s_cmp_eq_u32 s98, 2
	s_cbranch_scc1 .LBB0_333
	s_cmp_eq_u32 s98, 4
	s_cbranch_scc1 .Lmy_b372x
	v_mov_b32_e32 v0, v194
	s_and_b64 s[0:1], s[78:79], exec
	s_movk_i32 s0, 0xffe0
	v_readfirstlane_b32 s1, v0
	v_cvt_f32_u32_e32 v0, s7
	s_cselect_b32 s0, s0, 0xffffffd0
	s_sub_i32 s4, 0, s7
	s_add_i32 s0, s7, s0
	v_rcp_iflag_f32_e32 v0, v0
	s_add_i32 s0, s0, s6
	s_ashr_i32 s1, s1, 6
	v_mul_f32_e32 v0, 0x4f7ffffe, v0
	v_cvt_u32_f32_e32 v0, v0
	s_nop 0
	v_readfirstlane_b32 s5, v0
	s_mul_i32 s4, s4, s5
	s_mul_hi_u32 s4, s5, s4
	s_add_i32 s5, s5, s4
	s_mul_hi_u32 s4, s0, s5
	s_mul_i32 s4, s4, s7
	s_sub_i32 s0, s0, s4
	s_sub_i32 s4, s0, s7
	s_cmp_ge_u32 s0, s7
	s_cselect_b32 s0, s4, s0
	s_sub_i32 s4, s0, s7
	s_cmp_ge_u32 s0, s7
	s_cselect_b32 s18, s4, s0
	v_readlane_b32 s4, v234, 48
	s_mul_i32 s0, s4, 0x98000
	v_readlane_b32 s4, v235, 2
	v_readlane_b32 s5, v234, 49
	s_add_u32 s4, s4, s0
	v_readlane_b32 s0, v235, 3
	s_addc_u32 s5, s0, 0
	s_add_u32 s8, s4, 0x18000
	s_addc_u32 s9, s5, 0
	s_lshl_b32 s0, s18, 3
	s_add_i32 s19, s1, s0
	s_lshl_b32 s0, s59, 3
	s_sub_i32 s20, 0x800, s0
	s_branch .LBB0_321

.LBB0_333:
	s_cmp_eq_u32 s98, 1
	s_cbranch_scc0 .Lmy_post_go
	s_bitcmp1_b32 s6, 0
	s_cbranch_scc1 .Lmy_post3
	s_mov_b32 s98, 2
	s_branch .Lmy_conv_go
.Lmy_post3:
	s_mov_b32 s98, 3
	s_branch .Lmy_post_go2
.Lmy_post_go:
	s_mov_b32 s98, 0

.LBB0_372:
	s_cmp_eq_u32 s98, 3
	s_cbranch_scc0 .Lmy_b372
	s_mov_b32 s98, 4
	s_branch .Lmy_conv_go
